# prologue weight-conversion LN-fold loads batched as well
# speedup vs baseline: 1.0418x; 1.0026x over previous
.LBB0_76:
	s_or_b64 exec, exec, s[20:21]
	s_andn2_b64 vcc, exec, s[14:15]
	s_cbranch_vccnz .LBB0_80
	v_ashrrev_i32_e32 v13, 31, v12
	v_lshlrev_b64 v[12:13], 2, v[12:13]
	v_lshl_add_u64 v[14:15], s[6:7], 0, v[12:13]
	global_load_dword v89, v[14:15], off
	s_ashr_i32 s19, s18, 31
	v_lshl_add_u64 v[14:15], s[18:19], 0, v[2:3]
	v_lshl_add_u64 v[12:13], s[12:13], 0, v[12:13]
	v_lshlrev_b64 v[14:15], 2, v[14:15]
	global_load_dword v90, v[12:13], off
	v_lshl_add_u64 v[12:13], s[6:7], 0, v[14:15]
	v_lshl_add_u64 v[14:15], s[12:13], 0, v[14:15]
	global_load_dword v160, v[12:13], off offset:8
	global_load_dword v161, v[14:15], off offset:8
	global_load_dword v162, v[12:13], off offset:16
	global_load_dword v163, v[14:15], off offset:16
	global_load_dword v164, v[12:13], off offset:24
	global_load_dword v165, v[14:15], off offset:24
	global_load_dword v166, v[12:13], off offset:32
	global_load_dword v167, v[14:15], off offset:32
	global_load_dword v168, v[12:13], off offset:40
	global_load_dword v169, v[14:15], off offset:40
	global_load_dword v170, v[12:13], off offset:48
	global_load_dword v171, v[14:15], off offset:48
	global_load_dword v172, v[12:13], off offset:56
	global_load_dword v173, v[14:15], off offset:56
	global_load_dword v174, v[12:13], off offset:64
	global_load_dword v175, v[14:15], off offset:64
	global_load_dword v176, v[12:13], off offset:72
	global_load_dword v177, v[14:15], off offset:72
	global_load_dword v178, v[12:13], off offset:80
	global_load_dword v179, v[14:15], off offset:80
	global_load_dword v180, v[12:13], off offset:88
	global_load_dword v181, v[14:15], off offset:88
	global_load_dword v182, v[12:13], off offset:96
	global_load_dword v183, v[14:15], off offset:96
	global_load_dword v184, v[12:13], off offset:104
	global_load_dword v185, v[14:15], off offset:104
	global_load_dword v186, v[12:13], off offset:112
	global_load_dword v187, v[14:15], off offset:112
	global_load_dword v188, v[12:13], off offset:120
	global_load_dword v189, v[14:15], off offset:120
	global_load_dword v190, v[12:13], off offset:128
	global_load_dword v191, v[14:15], off offset:128
	global_load_dword v192, v[12:13], off offset:136
	global_load_dword v193, v[14:15], off offset:136
	global_load_dword v194, v[12:13], off offset:144
	global_load_dword v195, v[14:15], off offset:144
	global_load_dword v196, v[12:13], off offset:152
	global_load_dword v197, v[14:15], off offset:152
	global_load_dword v198, v[12:13], off offset:160
	global_load_dword v199, v[14:15], off offset:160
	global_load_dword v200, v[12:13], off offset:168
	global_load_dword v201, v[14:15], off offset:168
	global_load_dword v202, v[12:13], off offset:176
	global_load_dword v203, v[14:15], off offset:176
	global_load_dword v204, v[12:13], off offset:184
	global_load_dword v205, v[14:15], off offset:184
	global_load_dword v206, v[12:13], off offset:192
	global_load_dword v207, v[14:15], off offset:192
	global_load_dword v208, v[12:13], off offset:200
	global_load_dword v209, v[14:15], off offset:200
	global_load_dword v210, v[12:13], off offset:208
	global_load_dword v211, v[14:15], off offset:208
	global_load_dword v212, v[12:13], off offset:216
	global_load_dword v213, v[14:15], off offset:216
	global_load_dword v214, v[12:13], off offset:224
	global_load_dword v215, v[14:15], off offset:224
	global_load_dword v216, v[12:13], off offset:232
	global_load_dword v217, v[14:15], off offset:232
	global_load_dword v218, v[12:13], off offset:240
	global_load_dword v219, v[14:15], off offset:240
	global_load_dword v220, v[14:15], off offset:248
	global_load_dword v221, v[12:13], off offset:248
	s_waitcnt vmcnt(0) lgkmcnt(0)
	v_mul_f32_e32 v91, v57, v89
	ds_write_b32 v16, v91
	v_mov_b32_e32 v89, v160
	v_mov_b32_e32 v92, v161
	s_waitcnt vmcnt(0) lgkmcnt(0)
	v_mul_f32_e32 v93, v59, v89
	ds_write_b32 v17, v93
	v_mov_b32_e32 v89, v162
	v_mov_b32_e32 v94, v163
	s_waitcnt vmcnt(0) lgkmcnt(0)
	v_mul_f32_e32 v95, v58, v89
	ds_write_b32 v22, v95
	v_mov_b32_e32 v89, v164
	v_mov_b32_e32 v96, v165
	s_waitcnt vmcnt(0) lgkmcnt(0)
	v_mul_f32_e32 v97, v61, v89
	ds_write_b32 v23, v97
	v_mov_b32_e32 v89, v166
	v_mov_b32_e32 v98, v167
	s_waitcnt vmcnt(0) lgkmcnt(0)
	v_mul_f32_e32 v99, v60, v89
	ds_write_b32 v24, v99
	v_mov_b32_e32 v89, v168
	v_mov_b32_e32 v100, v169
	s_waitcnt vmcnt(0) lgkmcnt(0)
	v_mul_f32_e32 v101, v63, v89
	ds_write_b32 v25, v101
	v_mov_b32_e32 v89, v170
	v_mov_b32_e32 v102, v171
	s_waitcnt vmcnt(0) lgkmcnt(0)
	v_mul_f32_e32 v103, v62, v89
	ds_write_b32 v26, v103
	v_mov_b32_e32 v89, v172
	v_mov_b32_e32 v104, v173
	s_waitcnt vmcnt(0) lgkmcnt(0)
	v_mul_f32_e32 v105, v65, v89
	ds_write_b32 v27, v105
	v_mov_b32_e32 v89, v174
	v_mov_b32_e32 v106, v175
	s_waitcnt vmcnt(0) lgkmcnt(0)
	v_mul_f32_e32 v107, v64, v89
	ds_write_b32 v28, v107
	v_mov_b32_e32 v89, v176
	v_mov_b32_e32 v108, v177
	s_waitcnt vmcnt(0) lgkmcnt(0)
	v_mul_f32_e32 v109, v67, v89
	ds_write_b32 v29, v109
	v_mov_b32_e32 v89, v178
	v_mov_b32_e32 v110, v179
	s_waitcnt vmcnt(0) lgkmcnt(0)
	v_mul_f32_e32 v111, v66, v89
	ds_write_b32 v31, v111
	v_mov_b32_e32 v89, v180
	v_mov_b32_e32 v112, v181
	s_waitcnt vmcnt(0) lgkmcnt(0)
	v_mul_f32_e32 v113, v69, v89
	ds_write_b32 v34, v113
	v_mov_b32_e32 v89, v182
	v_mov_b32_e32 v114, v183
	s_waitcnt vmcnt(0) lgkmcnt(0)
	v_mul_f32_e32 v115, v68, v89
	ds_write_b32 v35, v115
	v_mov_b32_e32 v89, v184
	v_mov_b32_e32 v116, v185
	s_waitcnt vmcnt(0) lgkmcnt(0)
	v_mul_f32_e32 v117, v71, v89
	ds_write_b32 v36, v117
	v_mov_b32_e32 v89, v186
	v_mov_b32_e32 v118, v187
	s_waitcnt vmcnt(0) lgkmcnt(0)
	v_mul_f32_e32 v119, v70, v89
	ds_write_b32 v37, v119
	v_mov_b32_e32 v89, v188
	v_mov_b32_e32 v120, v189
	s_waitcnt vmcnt(0) lgkmcnt(0)
	v_mul_f32_e32 v121, v73, v89
	ds_write_b32 v38, v121
	v_mov_b32_e32 v89, v190
	v_mov_b32_e32 v122, v191
	s_waitcnt vmcnt(0) lgkmcnt(0)
	v_mul_f32_e32 v123, v72, v89
	ds_write_b32 v39, v123
	v_mov_b32_e32 v89, v192
	v_mov_b32_e32 v124, v193
	s_waitcnt vmcnt(0) lgkmcnt(0)
	v_mul_f32_e32 v125, v75, v89
	ds_write_b32 v40, v125
	v_mov_b32_e32 v89, v194
	v_mov_b32_e32 v126, v195
	s_waitcnt vmcnt(0) lgkmcnt(0)
	v_mul_f32_e32 v127, v74, v89
	ds_write_b32 v41, v127
	v_mov_b32_e32 v89, v196
	v_mov_b32_e32 v128, v197
	s_waitcnt vmcnt(0) lgkmcnt(0)
	v_mul_f32_e32 v129, v77, v89
	ds_write_b32 v42, v129
	v_mov_b32_e32 v89, v198
	v_mov_b32_e32 v130, v199
	s_waitcnt vmcnt(0) lgkmcnt(0)
	v_mul_f32_e32 v131, v76, v89
	ds_write_b32 v43, v131
	v_mov_b32_e32 v89, v200
	v_mov_b32_e32 v132, v201
	s_waitcnt vmcnt(0) lgkmcnt(0)
	v_mul_f32_e32 v133, v79, v89
	ds_write_b32 v44, v133
	v_mov_b32_e32 v89, v202
	v_mov_b32_e32 v134, v203
	s_waitcnt vmcnt(0) lgkmcnt(0)
	v_mul_f32_e32 v135, v78, v89
	ds_write_b32 v45, v135
	v_mov_b32_e32 v89, v204
	v_mov_b32_e32 v136, v205
	s_waitcnt vmcnt(0) lgkmcnt(0)
	v_mul_f32_e32 v137, v81, v89
	ds_write_b32 v46, v137
	v_mov_b32_e32 v89, v206
	v_mov_b32_e32 v138, v207
	s_waitcnt vmcnt(0) lgkmcnt(0)
	v_mul_f32_e32 v139, v80, v89
	ds_write_b32 v47, v139
	v_mov_b32_e32 v89, v208
	v_mov_b32_e32 v140, v209
	s_waitcnt vmcnt(0) lgkmcnt(0)
	v_mul_f32_e32 v141, v83, v89
	ds_write_b32 v48, v141
	v_mov_b32_e32 v89, v210
	v_mov_b32_e32 v142, v211
	s_waitcnt vmcnt(0) lgkmcnt(0)
	v_mul_f32_e32 v143, v82, v89
	ds_write_b32 v49, v143
	v_mov_b32_e32 v89, v212
	v_mov_b32_e32 v144, v213
	s_waitcnt vmcnt(0) lgkmcnt(0)
	v_mul_f32_e32 v145, v85, v89
	ds_write_b32 v50, v145
	v_mov_b32_e32 v89, v214
	v_mov_b32_e32 v146, v215
	s_waitcnt vmcnt(0) lgkmcnt(0)
	v_mul_f32_e32 v147, v84, v89
	ds_write_b32 v51, v147
	v_mov_b32_e32 v89, v216
	v_mov_b32_e32 v148, v217
	s_waitcnt vmcnt(0) lgkmcnt(0)
	v_mul_f32_e32 v149, v87, v89
	ds_write_b32 v52, v149
	v_mov_b32_e32 v150, v218
	v_fma_f32 v89, v57, v90, 0
	v_bfe_u32 v90, v91, 16, 1
	v_add3_u32 v90, v91, v90, s30
	v_bfe_u32 v91, v93, 16, 1
	v_and_b32_e32 v90, 0xffff0000, v90
	v_add3_u32 v91, v93, v91, s30
	v_add_f32_e32 v90, 0, v90
	v_and_b32_e32 v91, 0xffff0000, v91
	v_add_f32_e32 v90, v90, v91
	v_bfe_u32 v91, v95, 16, 1
	v_add3_u32 v91, v95, v91, s30
	v_and_b32_e32 v91, 0xffff0000, v91
	v_add_f32_e32 v90, v90, v91
	v_bfe_u32 v91, v97, 16, 1
	v_add3_u32 v91, v97, v91, s30
	v_and_b32_e32 v91, 0xffff0000, v91
	v_add_f32_e32 v90, v90, v91
	v_bfe_u32 v91, v99, 16, 1
	v_add3_u32 v91, v99, v91, s30
	v_and_b32_e32 v91, 0xffff0000, v91
	v_add_f32_e32 v90, v90, v91
	v_bfe_u32 v91, v101, 16, 1
	v_add3_u32 v91, v101, v91, s30
	v_and_b32_e32 v91, 0xffff0000, v91
	v_add_f32_e32 v90, v90, v91
	v_bfe_u32 v91, v103, 16, 1
	v_add3_u32 v91, v103, v91, s30
	v_and_b32_e32 v91, 0xffff0000, v91
	v_add_f32_e32 v90, v90, v91
	v_bfe_u32 v91, v105, 16, 1
	v_add3_u32 v91, v105, v91, s30
	v_and_b32_e32 v91, 0xffff0000, v91
	v_add_f32_e32 v90, v90, v91
	v_bfe_u32 v91, v107, 16, 1
	v_add3_u32 v91, v107, v91, s30
	v_and_b32_e32 v91, 0xffff0000, v91
	v_add_f32_e32 v90, v90, v91
	v_bfe_u32 v91, v109, 16, 1
	v_add3_u32 v91, v109, v91, s30
	v_and_b32_e32 v91, 0xffff0000, v91
	v_add_f32_e32 v90, v90, v91
	v_bfe_u32 v91, v111, 16, 1
	v_add3_u32 v91, v111, v91, s30
	v_and_b32_e32 v91, 0xffff0000, v91
	v_add_f32_e32 v90, v90, v91
	v_bfe_u32 v91, v113, 16, 1
	v_add3_u32 v91, v113, v91, s30
	v_and_b32_e32 v91, 0xffff0000, v91
	v_add_f32_e32 v90, v90, v91
	v_bfe_u32 v91, v115, 16, 1
	v_add3_u32 v91, v115, v91, s30
	v_and_b32_e32 v91, 0xffff0000, v91
	v_add_f32_e32 v90, v90, v91
	v_bfe_u32 v91, v117, 16, 1
	v_add3_u32 v91, v117, v91, s30
	v_and_b32_e32 v91, 0xffff0000, v91
	v_add_f32_e32 v90, v90, v91
	v_bfe_u32 v91, v119, 16, 1
	v_add3_u32 v91, v119, v91, s30
	v_and_b32_e32 v91, 0xffff0000, v91
	v_fmac_f32_e32 v89, v59, v92
	v_add_f32_e32 v90, v90, v91
	v_mov_b32_e32 v91, v219
	v_fmac_f32_e32 v89, v58, v94
	v_bfe_u32 v92, v121, 16, 1
	v_fmac_f32_e32 v89, v61, v96
	v_fmac_f32_e32 v89, v60, v98
	v_fmac_f32_e32 v89, v63, v100
	v_fmac_f32_e32 v89, v62, v102
	v_fmac_f32_e32 v89, v65, v104
	v_fmac_f32_e32 v89, v64, v106
	v_fmac_f32_e32 v89, v67, v108
	v_fmac_f32_e32 v89, v66, v110
	v_fmac_f32_e32 v89, v69, v112
	v_fmac_f32_e32 v89, v68, v114
	v_fmac_f32_e32 v89, v71, v116
	v_fmac_f32_e32 v89, v70, v118
	v_fmac_f32_e32 v89, v73, v120
	v_fmac_f32_e32 v89, v72, v122
	s_waitcnt vmcnt(0) lgkmcnt(0)
	v_mul_f32_e32 v93, v86, v150
	ds_write_b32 v53, v93
	v_mov_b32_e32 v94, v220
	v_mov_b32_e32 v95, v221
	v_add3_u32 v12, v121, v92, s30
	v_bfe_u32 v13, v123, 16, 1
	v_and_b32_e32 v12, 0xffff0000, v12
	v_add3_u32 v13, v123, v13, s30
	v_add_f32_e32 v12, v90, v12
	v_and_b32_e32 v13, 0xffff0000, v13
	v_add_f32_e32 v12, v12, v13
	v_bfe_u32 v13, v125, 16, 1
	v_add3_u32 v13, v125, v13, s30
	v_and_b32_e32 v13, 0xffff0000, v13
	v_add_f32_e32 v12, v12, v13
	v_bfe_u32 v13, v127, 16, 1
	v_add3_u32 v13, v127, v13, s30
	v_and_b32_e32 v13, 0xffff0000, v13
	v_add_f32_e32 v12, v12, v13
	v_bfe_u32 v13, v129, 16, 1
	v_add3_u32 v13, v129, v13, s30
	v_and_b32_e32 v13, 0xffff0000, v13
	v_add_f32_e32 v12, v12, v13
	v_bfe_u32 v13, v131, 16, 1
	v_add3_u32 v13, v131, v13, s30
	v_and_b32_e32 v13, 0xffff0000, v13
	v_add_f32_e32 v12, v12, v13
	v_bfe_u32 v13, v133, 16, 1
	v_add3_u32 v13, v133, v13, s30
	v_and_b32_e32 v13, 0xffff0000, v13
	v_add_f32_e32 v12, v12, v13
	v_bfe_u32 v13, v135, 16, 1
	v_add3_u32 v13, v135, v13, s30
	v_and_b32_e32 v13, 0xffff0000, v13
	v_add_f32_e32 v12, v12, v13
	v_bfe_u32 v13, v137, 16, 1
	v_add3_u32 v13, v137, v13, s30
	v_and_b32_e32 v13, 0xffff0000, v13
	v_add_f32_e32 v12, v12, v13
	v_bfe_u32 v13, v139, 16, 1
	v_add3_u32 v13, v139, v13, s30
	v_and_b32_e32 v13, 0xffff0000, v13
	v_add_f32_e32 v12, v12, v13
	v_bfe_u32 v13, v141, 16, 1
	v_add3_u32 v13, v141, v13, s30
	v_and_b32_e32 v13, 0xffff0000, v13
	v_add_f32_e32 v12, v12, v13
	v_bfe_u32 v13, v143, 16, 1
	v_add3_u32 v13, v143, v13, s30
	v_and_b32_e32 v13, 0xffff0000, v13
	v_add_f32_e32 v12, v12, v13
	v_bfe_u32 v13, v145, 16, 1
	v_fmac_f32_e32 v89, v75, v124
	v_add3_u32 v13, v145, v13, s30
	v_fmac_f32_e32 v89, v74, v126
	v_and_b32_e32 v13, 0xffff0000, v13
	v_fmac_f32_e32 v89, v77, v128
	v_add_f32_e32 v12, v12, v13
	v_bfe_u32 v13, v147, 16, 1
	v_fmac_f32_e32 v89, v76, v130
	v_add3_u32 v13, v147, v13, s30
	v_fmac_f32_e32 v89, v79, v132
	v_and_b32_e32 v13, 0xffff0000, v13
	v_fmac_f32_e32 v89, v78, v134
	v_add_f32_e32 v12, v12, v13
	v_bfe_u32 v13, v149, 16, 1
	v_fmac_f32_e32 v89, v81, v136
	v_add3_u32 v13, v149, v13, s30
	v_fmac_f32_e32 v89, v80, v138
	v_and_b32_e32 v13, 0xffff0000, v13
	v_fmac_f32_e32 v89, v83, v140
	v_add_f32_e32 v12, v12, v13
	v_bfe_u32 v13, v93, 16, 1
	v_fmac_f32_e32 v89, v82, v142
	v_add3_u32 v13, v93, v13, s30
	v_fmac_f32_e32 v89, v85, v144
	v_and_b32_e32 v13, 0xffff0000, v13
	v_fmac_f32_e32 v89, v84, v146
	v_add_f32_e32 v12, v12, v13
	v_fmac_f32_e32 v89, v87, v148
	v_fmac_f32_e32 v89, v86, v91
	s_waitcnt vmcnt(0) lgkmcnt(0)
	v_fmac_f32_e32 v89, v88, v94
	v_mul_f32_e32 v15, v88, v95
	v_bfe_u32 v13, v15, 16, 1
	v_add3_u32 v13, v15, v13, s30
	v_and_b32_e32 v13, 0xffff0000, v13
	v_add_f32_e32 v12, v12, v13
	ds_bpermute_b32 v13, v55, v12
	ds_bpermute_b32 v14, v55, v89
	ds_write_b32 v54, v15
	s_and_saveexec_b64 s[20:21], s[4:5]
	s_cbranch_execz .LBB0_79
	s_waitcnt lgkmcnt(2)
	v_add_f32_e32 v12, v12, v13
	v_mul_f32_e32 v12, 0x4f800000, v12
	s_waitcnt lgkmcnt(1)
	v_add_f32_e32 v89, v89, v14
	v_rndne_f32_e32 v14, v12
	v_mul_f32_e64 v12, |v14|, s31
	v_floor_f32_e32 v12, v12
	v_fma_f32 v13, v12, s38, |v14|
	v_cvt_u32_f32_e32 v90, v13
	v_cvt_u32_f32_e32 v15, v12
	v_ashrrev_i32_e32 v91, 31, v14
	s_ashr_i32 s17, s16, 31
	v_xor_b32_e32 v14, v90, v91
	s_lshl_b64 s[22:23], s[16:17], 3
	v_xor_b32_e32 v15, v15, v91
	v_sub_co_u32_e32 v14, vcc, v14, v91
	v_lshl_add_u64 v[12:13], v[6:7], 0, s[22:23]
	s_nop 0
	v_subb_co_u32_e32 v15, vcc, v15, v91, vcc
	flat_atomic_add_x2 v[12:13], v[14:15]
	v_mul_f32_e32 v12, 0x4f800000, v89
	v_rndne_f32_e32 v14, v12
	v_mul_f32_e64 v12, |v14|, s31
	v_floor_f32_e32 v12, v12
	v_fma_f32 v13, v12, s38, |v14|
	v_cvt_u32_f32_e32 v89, v13
	v_cvt_u32_f32_e32 v15, v12
	v_ashrrev_i32_e32 v90, 31, v14
	v_lshl_add_u64 v[12:13], v[8:9], 0, s[22:23]
	v_xor_b32_e32 v14, v89, v90
	v_xor_b32_e32 v15, v15, v90
	v_sub_co_u32_e32 v14, vcc, v14, v90
	s_nop 1
	v_subb_co_u32_e32 v15, vcc, v15, v90, vcc
	flat_atomic_add_x2 v[12:13], v[14:15]
